# summary pass tile back block: waits for next-tile loads no longer wait for the 7 local-state stores (vmcnt 10/8/7 instead of 3/1/0)
# speedup vs baseline: 1.0119x; 1.0047x over previous
.LBB0_425:
	s_or_b64 exec, exec, s[34:35]
	s_waitcnt lgkmcnt(0)
	v_pk_add_f32 v[16:17], v[98:99], 0 op_sel_hi:[1,0]
	v_pk_add_f32 v[98:99], v[100:101], 0 op_sel_hi:[1,0]
	v_pk_add_f32 v[16:17], v[16:17], v[110:111]
	v_pk_add_f32 v[98:99], v[98:99], v[0:1]
	v_pk_add_f32 v[0:1], v[102:103], 0 op_sel_hi:[1,0]
	s_add_i32 s39, s39, 16
	v_pk_add_f32 v[2:3], v[0:1], v[2:3]
	v_pk_add_f32 v[0:1], v[106:107], 0 op_sel_hi:[1,0]
	v_cvt_pk_bf16_f32 v2, v2, v3
	v_pk_add_f32 v[4:5], v[0:1], v[4:5]
	v_pk_add_f32 v[0:1], v[108:109], 0 op_sel_hi:[1,0]
	v_cvt_pk_bf16_f32 v3, v4, v5
	v_pk_add_f32 v[6:7], v[0:1], v[6:7]
	v_pk_add_f32 v[0:1], v[92:93], 0 op_sel_hi:[1,0]
	v_lshl_add_u64 v[4:5], v[112:113], 0, s[18:19]
	v_pk_add_f32 v[10:11], v[0:1], v[10:11]
	v_pk_add_f32 v[0:1], v[94:95], 0 op_sel_hi:[1,0]
	s_add_u32 s30, s30, 0x800
	v_pk_add_f32 v[14:15], v[0:1], v[14:15]
	v_pk_add_f32 v[0:1], v[88:89], 0 op_sel_hi:[1,0]
	v_mov_b32_e32 v88, v89
	v_pk_add_f32 v[12:13], v[0:1], v[12:13]
	v_cvt_pk_bf16_f32 v0, v16, v17
	v_cvt_pk_bf16_f32 v1, v98, v99
	global_store_dwordx4 v[112:113], v[0:3], off sc1
	s_nop 1
	v_cvt_pk_bf16_f32 v0, v6, v7
	v_cvt_pk_bf16_f32 v1, v10, v11
	v_cvt_pk_bf16_f32 v2, v14, v15
	v_cvt_pk_bf16_f32 v3, v12, v13
	global_store_dwordx4 v[4:5], v[0:3], off sc1
	s_nop 1
	v_cvt_pk_bf16_f32 v0, v96, v97
	v_cvt_pk_bf16_f32 v1, v203, v204
	v_cvt_pk_bf16_f32 v2, v205, v207
	v_cvt_pk_bf16_f32 v3, v208, v212
	v_lshl_add_u64 v[4:5], v[112:113], 0, s[12:13]
	global_store_dwordx4 v[4:5], v[0:3], off sc1
	s_nop 1
	v_cvt_pk_bf16_f32 v0, v206, v209
	v_cvt_pk_bf16_f32 v1, v211, v213
	v_cvt_pk_bf16_f32 v2, v217, v218
	v_cvt_pk_bf16_f32 v3, v219, v90
	v_lshl_add_u64 v[4:5], v[112:113], 0, s[20:21]
	global_store_dwordx4 v[4:5], v[0:3], off sc1
	s_nop 1
	v_cvt_pk_bf16_f32 v0, v91, v118
	v_cvt_pk_bf16_f32 v1, v117, v116
	v_cvt_pk_bf16_f32 v2, v115, v114
	v_cvt_pk_bf16_f32 v3, v105, v104
	v_lshl_add_u64 v[4:5], v[112:113], 0, s[14:15]
	global_store_dwordx4 v[4:5], v[0:3], off sc1
	s_nop 1
	v_cvt_pk_bf16_f32 v0, v23, v22
	v_cvt_pk_bf16_f32 v1, v21, v20
	v_cvt_pk_bf16_f32 v2, v19, v18
	v_cvt_pk_bf16_f32 v3, v8, v9
	v_lshl_add_u64 v[4:5], v[112:113], 0, s[8:9]
	global_store_dwordx4 v[4:5], v[0:3], off sc1
	s_nop 1
	v_lshl_add_u64 v[0:1], v[112:113], 0, s[16:17]
	v_mov_b32_e32 v89, v110
	global_store_dwordx4 v[0:1], v[88:91], off sc1
	s_nop 1
	s_addc_u32 s31, s31, 0
	s_mov_b64 s[34:35], 0x1c00
	s_waitcnt vmcnt(10)
	v_mov_b64_e32 v[0:1], v[84:85]
	v_mov_b64_e32 v[8:9], v[80:81]
	v_mov_b64_e32 v[90:91], v[70:71]
	v_mov_b64_e32 v[102:103], v[62:63]
	v_mov_b64_e32 v[12:13], v[76:77]
	v_mov_b64_e32 v[20:21], v[72:73]
	v_mov_b64_e32 v[94:95], v[66:67]
	v_mov_b64_e32 v[110:111], v[58:59]
	v_lshl_add_u64 v[112:113], v[112:113], 0, s[34:35]
	s_cmpk_lg_i32 s30, 0x2000
	s_waitcnt vmcnt(8)
	v_mov_b32_e32 v4, v201
	v_mov_b32_e32 v96, v198
	v_mov_b32_e32 v16, v200
	v_mov_b32_e32 v104, v197
	v_mov_b64_e32 v[2:3], v[86:87]
	v_mov_b64_e32 v[10:11], v[82:83]
	v_mov_b64_e32 v[88:89], v[68:69]
	v_mov_b64_e32 v[100:101], v[60:61]
	v_mov_b64_e32 v[14:15], v[78:79]
	v_mov_b64_e32 v[22:23], v[74:75]
	v_mov_b64_e32 v[92:93], v[64:65]
	v_mov_b64_e32 v[108:109], v[56:57]
	v_mov_b32_e32 v6, v199
	s_waitcnt vmcnt(7)
	v_mov_b32_e32 v148, v202
	s_cbranch_scc0 .LBB0_393
